# ret_local chunk-top touches for the end-of-chunk loads
# baseline (speedup 1.0000x reference)
; #define LAS __attribute__((address_space(3)))
; __device__ __forceinline__ unsigned cvt_pk_bf16(float lo, float hi) { const f32v2_t v = {lo, hi}; const bf16v2_t r = __builtin_convertvector(v, bf16v2_t); return __builtin_bit_cast(unsigned, r); }
; __device__ __forceinline__ float bflo(unsigned u) { return __uint_as_float(u << 16); }
; __device__ __forceinline__ float bfhi(unsigned u) { return __uint_as_float(u & 0xffff0000u); }
; __device__ __forceinline__ f32x4 mfma16(bf16x8 a, bf16x8 b, f32x4 c) { return __builtin_amdgcn_mfma_f32_16x16x32_bf16(a, b, c, 0, 0, 0); }
; template <int NS> __device__ __forceinline__ void ret_local_unitN(LAS unsigned char* lds, const Params& P, int unit) {
;     ...
; #pragma unroll
;         for (int i = 0; i < 4; ++i) { const int ch = tid + 512 * i, r = ch >> 5, cc = ch & 31; *(LAS u32x4*)(TK + r * QS + cc * 16) = rk[i]; }
; #pragma unroll
;         for (int i = 0; i < NS; ++i) { const int ch = tid + 512 * i, r = ch / VCH, cc = ch % VCH;
;             const float d = exp2f((float)(63 - r) * lg2);
;             u32x4 vd;
; #pragma unroll
;             for (int j = 0; j < 4; ++j) vd[j] = cvt_pk_bf16(bflo(rv[i][j]) * d, bfhi(rv[i][j]) * d);
;             *(LAS u32x4*)(TVD + r * VSN + cc * 16) = vd; }
;         __syncthreads();
;         if (c + 1 < 16) RLN_LOAD(c + 1);
; #pragma unroll
;         for (int i = 0; i < 2; ++i)
; #pragma unroll
;             for (int nt = 0; nt < NT; ++nt) R[i][nt] = R[i][nt] * g64;
; #pragma unroll
;         for (int ks = 0; ks < 2; ++ks) {
;             const bf16x8 a0 = trfrag(TK, QS, 32 * ks, 16 * (2 * w), lane), a1 = trfrag(TK, QS, 32 * ks, 16 * (2 * w + 1), lane);
; #pragma unroll
;             for (int nt = 0; nt < NT; ++nt) { const bf16x8 bv = trfrag(TVD, VSN, 32 * ks, 16 * nt, lane); R[0][nt] = mfma16(a0, bv, R[0][nt]); R[1][nt] = mfma16(a1, bv, R[1][nt]); }
.LBB0_72:
	s_waitcnt vmcnt(7)
	ds_write_b128 v197, v[136:139]
	s_waitcnt vmcnt(6)
	ds_write_b128 v198, v[140:143]
	s_waitcnt vmcnt(5)
	ds_write_b128 v199, v[148:151]
	s_waitcnt vmcnt(4)
	ds_write_b128 v200, v[152:155]
	s_waitcnt vmcnt(3)
	v_lshlrev_b32_e32 v136, 16, v156
	v_and_b32_e32 v137, 0xffff0000, v156
	v_lshlrev_b32_e32 v138, 16, v157
	v_and_b32_e32 v139, 0xffff0000, v157
	v_pk_mul_f32 v[136:137], v[170:171], v[136:137]
	v_pk_mul_f32 v[138:139], v[170:171], v[138:139]
	v_cvt_pk_bf16_f32 v136, v136, v137
	v_cvt_pk_bf16_f32 v137, v138, v139
	v_lshlrev_b32_e32 v138, 16, v158
	v_and_b32_e32 v139, 0xffff0000, v158
	v_lshlrev_b32_e32 v140, 16, v159
	v_and_b32_e32 v141, 0xffff0000, v159
	v_pk_mul_f32 v[138:139], v[170:171], v[138:139]
	v_pk_mul_f32 v[140:141], v[170:171], v[140:141]
	v_cvt_pk_bf16_f32 v138, v138, v139
	v_cvt_pk_bf16_f32 v139, v140, v141
	ds_write_b128 v196, v[136:139] offset:34816
	s_waitcnt vmcnt(2)
	v_lshlrev_b32_e32 v136, 16, v132
	v_and_b32_e32 v137, 0xffff0000, v132
	v_pk_mul_f32 v[136:137], v[168:169], v[136:137]
	v_mov_b32_e32 v161, v160
	v_cvt_pk_bf16_f32 v132, v136, v137
	v_lshlrev_b32_e32 v136, 16, v133
	v_and_b32_e32 v137, 0xffff0000, v133
	v_pk_mul_f32 v[136:137], v[168:169], v[136:137]
	v_pk_mul_f32 v[106:107], v[160:161], v[106:107]
	v_cvt_pk_bf16_f32 v133, v136, v137
	v_lshlrev_b32_e32 v136, 16, v134
	v_and_b32_e32 v137, 0xffff0000, v134
	v_pk_mul_f32 v[136:137], v[168:169], v[136:137]
	v_pk_mul_f32 v[104:105], v[162:163], v[104:105]
	v_cvt_pk_bf16_f32 v134, v136, v137
	v_lshlrev_b32_e32 v136, 16, v135
	v_and_b32_e32 v137, 0xffff0000, v135
	v_pk_mul_f32 v[136:137], v[168:169], v[136:137]
	v_pk_mul_f32 v[122:123], v[160:161], v[122:123]
	v_cvt_pk_bf16_f32 v135, v136, v137
	ds_write_b128 v195, v[132:135] offset:34816
	s_waitcnt vmcnt(1)
	v_lshlrev_b32_e32 v132, 16, v128
	v_and_b32_e32 v133, 0xffff0000, v128
	v_pk_mul_f32 v[132:133], v[166:167], v[132:133]
	v_pk_mul_f32 v[120:121], v[162:163], v[120:121]
	v_cvt_pk_bf16_f32 v128, v132, v133
	v_lshlrev_b32_e32 v132, 16, v129
	v_and_b32_e32 v133, 0xffff0000, v129
	v_pk_mul_f32 v[132:133], v[166:167], v[132:133]
	v_pk_mul_f32 v[102:103], v[160:161], v[102:103]
	v_cvt_pk_bf16_f32 v129, v132, v133
	v_lshlrev_b32_e32 v132, 16, v130
	v_and_b32_e32 v133, 0xffff0000, v130
	v_pk_mul_f32 v[132:133], v[166:167], v[132:133]
	v_pk_mul_f32 v[100:101], v[162:163], v[100:101]
	v_cvt_pk_bf16_f32 v130, v132, v133
	v_lshlrev_b32_e32 v132, 16, v131
	v_and_b32_e32 v133, 0xffff0000, v131
	v_pk_mul_f32 v[132:133], v[166:167], v[132:133]
	v_pk_mul_f32 v[114:115], v[160:161], v[114:115]
	v_cvt_pk_bf16_f32 v131, v132, v133
	ds_write_b128 v194, v[128:131] offset:34816
	s_waitcnt vmcnt(0)
	v_lshlrev_b32_e32 v128, 16, v124
	v_and_b32_e32 v129, 0xffff0000, v124
	v_pk_mul_f32 v[128:129], v[164:165], v[128:129]
	v_pk_mul_f32 v[112:113], v[162:163], v[112:113]
	v_cvt_pk_bf16_f32 v124, v128, v129
	v_lshlrev_b32_e32 v128, 16, v125
	v_and_b32_e32 v129, 0xffff0000, v125
	v_pk_mul_f32 v[128:129], v[164:165], v[128:129]
	v_pk_mul_f32 v[98:99], v[160:161], v[98:99]
	v_cvt_pk_bf16_f32 v125, v128, v129
	v_lshlrev_b32_e32 v128, 16, v126
	v_and_b32_e32 v129, 0xffff0000, v126
	v_pk_mul_f32 v[128:129], v[164:165], v[128:129]
	v_pk_mul_f32 v[96:97], v[162:163], v[96:97]
	v_cvt_pk_bf16_f32 v126, v128, v129
	v_lshlrev_b32_e32 v128, 16, v127
	v_and_b32_e32 v129, 0xffff0000, v127
	v_pk_mul_f32 v[128:129], v[164:165], v[128:129]
	v_pk_mul_f32 v[110:111], v[160:161], v[110:111]
	v_cvt_pk_bf16_f32 v127, v128, v129
	ds_write_b128 v193, v[124:127] offset:34816
	s_waitcnt lgkmcnt(0)
	s_barrier
	v_lshl_add_u64 v[222:223], v[188:189], 0, s[0:1]
	global_load_dword v224, v[222:223], off
	v_lshl_add_u64 v[222:223], v[186:187], 0, s[0:1]
	global_load_dword v224, v[222:223], off
	v_lshl_add_u64 v[222:223], v[184:185], 0, s[0:1]
	global_load_dword v224, v[222:223], off
	v_lshl_add_u64 v[222:223], v[182:183], 0, s[0:1]
	global_load_dword v224, v[222:223], off
	v_lshl_add_u64 v[222:223], v[178:179], 0, s[0:1]
	global_load_dword v224, v[222:223], off
	v_lshl_add_u64 v[222:223], v[176:177], 0, s[0:1]
	global_load_dword v224, v[222:223], off
	v_lshl_add_u64 v[222:223], v[174:175], 0, s[0:1]
	global_load_dword v224, v[222:223], off
	v_lshl_add_u64 v[222:223], v[172:173], 0, s[0:1]
	global_load_dword v224, v[222:223], off
	v_pk_mul_f32 v[126:127], v[160:161], v[146:147]
	v_pk_mul_f32 v[124:125], v[162:163], v[144:145]
	ds_read_b64_tr_b16 v[130:131], v180 offset:2176
	ds_read_b64_tr_b16 v[128:129], v180
	ds_read_b64_tr_b16 v[134:135], v180 offset:2208
	ds_read_b64_tr_b16 v[132:133], v180 offset:32
	ds_read_b64_tr_b16 v[138:139], v192 offset:36992
	ds_read_b64_tr_b16 v[136:137], v192 offset:34816
	ds_read_b64_tr_b16 v[140:141], v192 offset:34848
	ds_read_b64_tr_b16 v[144:145], v192 offset:34880
	ds_read_b64_tr_b16 v[148:149], v192 offset:34912
	ds_read_b64_tr_b16 v[142:143], v192 offset:37024
	ds_read_b64_tr_b16 v[146:147], v192 offset:37056
	ds_read_b64_tr_b16 v[150:151], v192 offset:37088
	v_pk_mul_f32 v[108:109], v[162:163], v[108:109]
	v_pk_mul_f32 v[90:91], v[160:161], v[90:91]
	v_pk_mul_f32 v[88:89], v[162:163], v[88:89]
	s_waitcnt lgkmcnt(6)
	v_mfma_f32_16x16x32_bf16 v[124:127], v[128:131], v[136:139], v[124:127]
	v_mul_f32_e64 v118, v160, v118
	v_mul_f32_e64 v119, v161, v119
	v_pk_mul_f32 v[116:117], v[162:163], v[116:117]
	v_pk_mul_f32 v[74:75], v[160:161], v[74:75]
	v_mfma_f32_16x16x32_bf16 v[104:107], v[132:135], v[136:139], v[104:107]
	v_mul_f32_e64 v72, v162, v72
	v_mul_f32_e64 v73, v163, v73
	v_pk_mul_f32 v[94:95], v[160:161], v[94:95]
	v_pk_mul_f32 v[92:93], v[162:163], v[92:93]
	s_waitcnt lgkmcnt(2)
; __device__ __forceinline__ f32x4 mfma16(bf16x8 a, bf16x8 b, f32x4 c) { return __builtin_amdgcn_mfma_f32_16x16x32_bf16(a, b, c, 0, 0, 0); }
; template <int NS> __device__ __forceinline__ void ret_local_unitN(LAS unsigned char* lds, const Params& P, int unit) {
;     ...
;         for (int ks = 0; ks < 2; ++ks) {
;             const bf16x8 a0 = trfrag(TK, QS, 32 * ks, 16 * (2 * w), lane), a1 = trfrag(TK, QS, 32 * ks, 16 * (2 * w + 1), lane);
; #pragma unroll
;             for (int nt = 0; nt < NT; ++nt) { const bf16x8 bv = trfrag(TVD, VSN, 32 * ks, 16 * nt, lane); R[0][nt] = mfma16(a0, bv, R[0][nt]); R[1][nt] = mfma16(a1, bv, R[1][nt]); }
	v_mfma_f32_16x16x32_bf16 v[120:123], v[128:131], v[140:143], v[120:123]
	v_mul_f32_e64 v70, v160, v70
	v_mul_f32_e64 v71, v161, v71
	v_pk_mul_f32 v[68:69], v[162:163], v[68:69]
	v_pk_mul_f32 v[82:83], v[160:161], v[82:83]
	v_mfma_f32_16x16x32_bf16 v[100:103], v[132:135], v[140:143], v[100:103]
	v_mul_f32_e64 v80, v162, v80
	v_mul_f32_e64 v81, v163, v81
	v_pk_mul_f32 v[66:67], v[160:161], v[66:67]
	v_pk_mul_f32 v[64:65], v[162:163], v[64:65]
	s_waitcnt lgkmcnt(1)
	v_mfma_f32_16x16x32_bf16 v[112:115], v[128:131], v[144:147], v[112:115]
	v_mul_f32_e64 v78, v160, v78
	v_mul_f32_e64 v79, v161, v79
	v_pk_mul_f32 v[76:77], v[162:163], v[76:77]
	v_pk_mul_f32 v[58:59], v[160:161], v[58:59]
	v_mfma_f32_16x16x32_bf16 v[96:99], v[132:135], v[144:147], v[96:99]
	v_mul_f32_e64 v56, v162, v56
	v_mul_f32_e64 v57, v163, v57
	v_pk_mul_f32 v[86:87], v[160:161], v[86:87]
	v_pk_mul_f32 v[84:85], v[162:163], v[84:85]
	s_waitcnt lgkmcnt(0)
	v_mfma_f32_16x16x32_bf16 v[108:111], v[128:131], v[148:151], v[108:111]
	v_mul_f32_e64 v42, v160, v42
	v_mul_f32_e64 v43, v161, v43
	v_pk_mul_f32 v[40:41], v[162:163], v[40:41]
	v_pk_mul_f32 v[62:63], v[160:161], v[62:63]
	v_mfma_f32_16x16x32_bf16 v[88:91], v[132:135], v[148:151], v[88:91]
	ds_read_b64_tr_b16 v[138:139], v192 offset:37120
	ds_read_b64_tr_b16 v[136:137], v192 offset:34944
	ds_read_b64_tr_b16 v[140:141], v192 offset:34976
	ds_read_b64_tr_b16 v[144:145], v192 offset:35008
	ds_read_b64_tr_b16 v[148:149], v192 offset:35040
	ds_read_b64_tr_b16 v[142:143], v192 offset:37152
	ds_read_b64_tr_b16 v[146:147], v192 offset:37184
	ds_read_b64_tr_b16 v[150:151], v192 offset:37216
	v_pk_mul_f32 v[60:61], v[162:163], v[60:61]
	v_pk_mul_f32 v[38:39], v[160:161], v[38:39]
	s_waitcnt lgkmcnt(6)
	v_mfma_f32_16x16x32_bf16 v[116:119], v[128:131], v[136:139], v[116:119]
	v_mul_f32_e64 v36, v162, v36
	v_mul_f32_e64 v37, v163, v37
	v_pk_mul_f32 v[50:51], v[160:161], v[50:51]
	v_pk_mul_f32 v[48:49], v[162:163], v[48:49]
	v_mfma_f32_16x16x32_bf16 v[72:75], v[132:135], v[136:139], v[72:75]
	v_mul_f32_e64 v34, v160, v34
	v_mul_f32_e64 v35, v161, v35
	v_pk_mul_f32 v[32:33], v[162:163], v[32:33]
	v_pk_mul_f32 v[46:47], v[160:161], v[46:47]
	s_waitcnt lgkmcnt(2)
	v_mfma_f32_16x16x32_bf16 v[92:95], v[128:131], v[140:143], v[92:95]
	v_mul_f32_e64 v44, v162, v44
	v_mul_f32_e64 v45, v163, v45
	v_pk_mul_f32 v[26:27], v[160:161], v[26:27]
	v_pk_mul_f32 v[24:25], v[162:163], v[24:25]
	v_mfma_f32_16x16x32_bf16 v[68:71], v[132:135], v[140:143], v[68:71]
	v_mul_f32_e64 v54, v160, v54
	v_mul_f32_e64 v55, v161, v55
	v_pk_mul_f32 v[52:53], v[162:163], v[52:53]
	v_pk_mul_f32 v[14:15], v[160:161], v[14:15]
	s_waitcnt lgkmcnt(1)
	v_mfma_f32_16x16x32_bf16 v[80:83], v[128:131], v[144:147], v[80:83]
	v_mul_f32_e64 v12, v162, v12
	v_mul_f32_e64 v13, v163, v13
	v_pk_mul_f32 v[30:31], v[160:161], v[30:31]
	v_pk_mul_f32 v[28:29], v[162:163], v[28:29]
	v_mfma_f32_16x16x32_bf16 v[64:67], v[132:135], v[144:147], v[64:67]
	v_mul_f32_e64 v10, v160, v10
	v_mul_f32_e64 v11, v161, v11
	v_pk_mul_f32 v[8:9], v[162:163], v[8:9]
	v_pk_mul_f32 v[22:23], v[160:161], v[22:23]
	s_waitcnt lgkmcnt(0)
	v_mfma_f32_16x16x32_bf16 v[76:79], v[128:131], v[148:151], v[76:79]
	v_mul_f32_e64 v20, v162, v20
	v_mul_f32_e64 v21, v163, v21
	v_pk_mul_f32 v[6:7], v[160:161], v[6:7]
	v_pk_mul_f32 v[4:5], v[162:163], v[4:5]
	v_mfma_f32_16x16x32_bf16 v[56:59], v[132:135], v[148:151], v[56:59]
	ds_read_b64_tr_b16 v[138:139], v192 offset:37248
	ds_read_b64_tr_b16 v[136:137], v192 offset:35072
	ds_read_b64_tr_b16 v[140:141], v192 offset:35104
	ds_read_b64_tr_b16 v[144:145], v192 offset:35136
	ds_read_b64_tr_b16 v[148:149], v192 offset:35168
	ds_read_b64_tr_b16 v[142:143], v192 offset:37280
	ds_read_b64_tr_b16 v[146:147], v192 offset:37312
	ds_read_b64_tr_b16 v[150:151], v192 offset:37344
	v_pk_mul_f32 v[18:19], v[160:161], v[18:19]
	v_pk_mul_f32 v[16:17], v[162:163], v[16:17]
	s_waitcnt lgkmcnt(6)
	v_mfma_f32_16x16x32_bf16 v[84:87], v[128:131], v[136:139], v[84:87]
	v_mul_f32_e64 v2, v160, v2
	v_mul_f32_e64 v3, v161, v3
	v_pk_mul_f32 v[0:1], v[162:163], v[0:1]
	v_mfma_f32_16x16x32_bf16 v[40:43], v[132:135], v[136:139], v[40:43]
	s_waitcnt lgkmcnt(2)
	v_mfma_f32_16x16x32_bf16 v[60:63], v[128:131], v[140:143], v[60:63]
	v_mfma_f32_16x16x32_bf16 v[36:39], v[132:135], v[140:143], v[36:39]
	s_waitcnt lgkmcnt(1)
	v_mfma_f32_16x16x32_bf16 v[48:51], v[128:131], v[144:147], v[48:51]
	v_mfma_f32_16x16x32_bf16 v[32:35], v[132:135], v[144:147], v[32:35]
	s_waitcnt lgkmcnt(0)
	v_mfma_f32_16x16x32_bf16 v[44:47], v[128:131], v[148:151], v[44:47]
	v_mfma_f32_16x16x32_bf16 v[24:27], v[132:135], v[148:151], v[24:27]
	ds_read_b64_tr_b16 v[138:139], v192 offset:37376
	ds_read_b64_tr_b16 v[136:137], v192 offset:35200
	ds_read_b64_tr_b16 v[140:141], v192 offset:35232
	ds_read_b64_tr_b16 v[144:145], v192 offset:35264
	ds_read_b64_tr_b16 v[148:149], v192 offset:35296
	ds_read_b64_tr_b16 v[142:143], v192 offset:37408
	ds_read_b64_tr_b16 v[146:147], v192 offset:37440
	ds_read_b64_tr_b16 v[150:151], v192 offset:37472
	s_waitcnt lgkmcnt(6)
	v_mfma_f32_16x16x32_bf16 v[52:55], v[128:131], v[136:139], v[52:55]
	v_mfma_f32_16x16x32_bf16 v[12:15], v[132:135], v[136:139], v[12:15]
	s_waitcnt lgkmcnt(2)
	v_mfma_f32_16x16x32_bf16 v[28:31], v[128:131], v[140:143], v[28:31]
	v_mfma_f32_16x16x32_bf16 v[8:11], v[132:135], v[140:143], v[8:11]
	s_waitcnt lgkmcnt(1)
	v_mfma_f32_16x16x32_bf16 v[20:23], v[128:131], v[144:147], v[20:23]
	v_mfma_f32_16x16x32_bf16 v[4:7], v[132:135], v[144:147], v[4:7]
	s_waitcnt lgkmcnt(0)
; __device__ __forceinline__ f32x4 mfma16(bf16x8 a, bf16x8 b, f32x4 c) { return __builtin_amdgcn_mfma_f32_16x16x32_bf16(a, b, c, 0, 0, 0); }
; template <int NS> __device__ __forceinline__ void ret_local_unitN(LAS unsigned char* lds, const Params& P, int unit) {
;     ...
;         if (c + 1 < 16) RLN_LOAD(c + 1);
; #pragma unroll
;         for (int i = 0; i < 2; ++i)
; #pragma unroll
;             for (int nt = 0; nt < NT; ++nt) R[i][nt] = R[i][nt] * g64;
; #pragma unroll
;         for (int ks = 0; ks < 2; ++ks) {
;             const bf16x8 a0 = trfrag(TK, QS, 32 * ks, 16 * (2 * w), lane), a1 = trfrag(TK, QS, 32 * ks, 16 * (2 * w + 1), lane);
; #pragma unroll
;             for (int nt = 0; nt < NT; ++nt) { const bf16x8 bv = trfrag(TVD, VSN, 32 * ks, 16 * nt, lane); R[0][nt] = mfma16(a0, bv, R[0][nt]); R[1][nt] = mfma16(a1, bv, R[1][nt]); }
;         }
;         __syncthreads();
	v_mfma_f32_16x16x32_bf16 v[16:19], v[128:131], v[148:151], v[16:19]
	v_mfma_f32_16x16x32_bf16 v[0:3], v[132:135], v[148:151], v[0:3]
	ds_read_b64_tr_b16 v[128:129], v180 offset:17408
	ds_read_b64_tr_b16 v[130:131], v180 offset:19584
	ds_read_b64_tr_b16 v[216:217], v180 offset:19616
	ds_read_b64_tr_b16 v[214:215], v180 offset:17440
	ds_read_b64_tr_b16 v[134:135], v192 offset:54400
	ds_read_b64_tr_b16 v[132:133], v192 offset:52224
	ds_read_b64_tr_b16 v[136:137], v192 offset:52256
	ds_read_b64_tr_b16 v[140:141], v192 offset:52288
	ds_read_b64_tr_b16 v[148:149], v192 offset:52320
	ds_read_b64_tr_b16 v[138:139], v192 offset:54432
	ds_read_b64_tr_b16 v[142:143], v192 offset:54464
	ds_read_b64_tr_b16 v[150:151], v192 offset:54496
	s_waitcnt lgkmcnt(6)
	v_mfma_f32_16x16x32_bf16 v[144:147], v[128:131], v[132:135], v[124:127]
	v_mfma_f32_16x16x32_bf16 v[104:107], v[214:217], v[132:135], v[104:107]
	s_waitcnt lgkmcnt(2)
	v_mfma_f32_16x16x32_bf16 v[120:123], v[128:131], v[136:139], v[120:123]
	v_mfma_f32_16x16x32_bf16 v[100:103], v[214:217], v[136:139], v[100:103]
	s_waitcnt lgkmcnt(1)
	v_mfma_f32_16x16x32_bf16 v[112:115], v[128:131], v[140:143], v[112:115]
	v_mfma_f32_16x16x32_bf16 v[96:99], v[214:217], v[140:143], v[96:99]
	ds_read_b64_tr_b16 v[126:127], v192 offset:54528
	ds_read_b64_tr_b16 v[124:125], v192 offset:52352
	ds_read_b64_tr_b16 v[132:133], v192 offset:52384
	ds_read_b64_tr_b16 v[136:137], v192 offset:52416
	ds_read_b64_tr_b16 v[140:141], v192 offset:52448
	ds_read_b64_tr_b16 v[134:135], v192 offset:54560
	ds_read_b64_tr_b16 v[138:139], v192 offset:54592
	ds_read_b64_tr_b16 v[142:143], v192 offset:54624
	s_waitcnt lgkmcnt(6)
	v_mfma_f32_16x16x32_bf16 v[116:119], v[128:131], v[124:127], v[116:119]
	v_mfma_f32_16x16x32_bf16 v[72:75], v[214:217], v[124:127], v[72:75]
	s_waitcnt lgkmcnt(2)
	v_mfma_f32_16x16x32_bf16 v[92:95], v[128:131], v[132:135], v[92:95]
	v_mfma_f32_16x16x32_bf16 v[68:71], v[214:217], v[132:135], v[68:71]
	s_waitcnt lgkmcnt(1)
	v_mfma_f32_16x16x32_bf16 v[80:83], v[128:131], v[136:139], v[80:83]
	v_mfma_f32_16x16x32_bf16 v[64:67], v[214:217], v[136:139], v[64:67]
	s_waitcnt lgkmcnt(0)
	v_mfma_f32_16x16x32_bf16 v[76:79], v[128:131], v[140:143], v[76:79]
	v_mfma_f32_16x16x32_bf16 v[56:59], v[214:217], v[140:143], v[56:59]
	ds_read_b64_tr_b16 v[126:127], v192 offset:54656
	ds_read_b64_tr_b16 v[124:125], v192 offset:52480
	ds_read_b64_tr_b16 v[132:133], v192 offset:52512
	ds_read_b64_tr_b16 v[136:137], v192 offset:52544
	ds_read_b64_tr_b16 v[140:141], v192 offset:52576
	ds_read_b64_tr_b16 v[134:135], v192 offset:54688
	ds_read_b64_tr_b16 v[138:139], v192 offset:54720
	ds_read_b64_tr_b16 v[142:143], v192 offset:54752
	s_waitcnt lgkmcnt(6)
	v_mfma_f32_16x16x32_bf16 v[84:87], v[128:131], v[124:127], v[84:87]
	v_mfma_f32_16x16x32_bf16 v[40:43], v[214:217], v[124:127], v[40:43]
	s_waitcnt lgkmcnt(2)
	v_mfma_f32_16x16x32_bf16 v[60:63], v[128:131], v[132:135], v[60:63]
	v_mfma_f32_16x16x32_bf16 v[36:39], v[214:217], v[132:135], v[36:39]
	ds_read_b64_tr_b16 v[126:127], v192 offset:54784
	ds_read_b64_tr_b16 v[124:125], v192 offset:52608
	ds_read_b64_tr_b16 v[132:133], v192 offset:52640
	ds_read_b64_tr_b16 v[156:157], v192 offset:52672
	ds_read_b64_tr_b16 v[218:219], v192 offset:52704
	ds_read_b64_tr_b16 v[134:135], v192 offset:54816
	ds_read_b64_tr_b16 v[158:159], v192 offset:54848
	ds_read_b64_tr_b16 v[220:221], v192 offset:54880
	s_waitcnt lgkmcnt(6)
	v_mfma_f32_16x16x32_bf16 v[52:55], v[128:131], v[124:127], v[52:55]
	v_mfma_f32_16x16x32_bf16 v[12:15], v[214:217], v[124:127], v[12:15]
	v_lshl_add_u64 v[124:125], v[188:189], 0, s[0:1]
	v_lshl_add_u64 v[126:127], v[186:187], 0, s[0:1]
	v_mfma_f32_16x16x32_bf16 v[48:51], v[128:131], v[136:139], v[48:51]
	v_mfma_f32_16x16x32_bf16 v[32:35], v[214:217], v[136:139], v[32:35]
	v_mfma_f32_16x16x32_bf16 v[44:47], v[128:131], v[140:143], v[44:47]
	v_mfma_f32_16x16x32_bf16 v[24:27], v[214:217], v[140:143], v[24:27]
	global_load_dwordx4 v[136:139], v[124:125], off
	global_load_dwordx4 v[140:143], v[126:127], off
	v_lshl_add_u64 v[124:125], v[184:185], 0, s[0:1]
	v_lshl_add_u64 v[126:127], v[182:183], 0, s[0:1]
	v_mfma_f32_16x16x32_bf16 v[108:111], v[128:131], v[148:151], v[108:111]
	v_mfma_f32_16x16x32_bf16 v[88:91], v[214:217], v[148:151], v[88:91]
	global_load_dwordx4 v[148:151], v[124:125], off
	global_load_dwordx4 v[152:155], v[126:127], off
	v_lshl_add_u64 v[124:125], v[178:179], 0, s[0:1]
	v_lshl_add_u64 v[126:127], v[176:177], 0, s[0:1]
	s_waitcnt lgkmcnt(2)
	v_mfma_f32_16x16x32_bf16 v[28:31], v[128:131], v[132:135], v[28:31]
	v_mfma_f32_16x16x32_bf16 v[8:11], v[214:217], v[132:135], v[8:11]
	s_waitcnt lgkmcnt(1)
	v_mfma_f32_16x16x32_bf16 v[20:23], v[128:131], v[156:159], v[20:23]
	v_mfma_f32_16x16x32_bf16 v[4:7], v[214:217], v[156:159], v[4:7]
	global_load_dwordx4 v[156:159], v[124:125], off
	global_load_dwordx4 v[132:135], v[126:127], off
	v_lshl_add_u64 v[124:125], v[174:175], 0, s[0:1]
	v_lshl_add_u64 v[126:127], v[172:173], 0, s[0:1]
	s_waitcnt lgkmcnt(0)
	v_mfma_f32_16x16x32_bf16 v[16:19], v[128:131], v[218:221], v[16:19]
	global_load_dwordx4 v[128:131], v[124:125], off
	s_nop 0
	global_load_dwordx4 v[124:127], v[126:127], off
	s_add_u32 s0, s0, 0x180000
	s_addc_u32 s1, s1, 0
	v_mfma_f32_16x16x32_bf16 v[0:3], v[214:217], v[218:221], v[0:3]
	s_cmp_lg_u32 s0, 0x1680000
	s_barrier
	s_cbranch_scc1 .LBB0_72
; #define LAS __attribute__((address_space(3)))
; __device__ __forceinline__ unsigned cvt_pk_bf16(float lo, float hi) { const f32v2_t v = {lo, hi}; const bf16v2_t r = __builtin_convertvector(v, bf16v2_t); return __builtin_bit_cast(unsigned, r); }
; __device__ __forceinline__ float bflo(unsigned u) { return __uint_as_float(u << 16); }
; __device__ __forceinline__ float bfhi(unsigned u) { return __uint_as_float(u & 0xffff0000u); }
; __device__ __forceinline__ f32x4 mfma16(bf16x8 a, bf16x8 b, f32x4 c) { return __builtin_amdgcn_mfma_f32_16x16x32_bf16(a, b, c, 0, 0, 0); }
; template <int NS> __device__ __forceinline__ void ret_local_unitN(LAS unsigned char* lds, const Params& P, int unit) {
;     ...
; #pragma unroll
;         for (int i = 0; i < 4; ++i) { const int ch = tid + 512 * i, r = ch >> 5, cc = ch & 31; *(LAS u32x4*)(TK + r * QS + cc * 16) = rk[i]; }
; #pragma unroll
;         for (int i = 0; i < NS; ++i) { const int ch = tid + 512 * i, r = ch / VCH, cc = ch % VCH;
;             const float d = exp2f((float)(63 - r) * lg2);
;             u32x4 vd;
; #pragma unroll
;             for (int j = 0; j < 4; ++j) vd[j] = cvt_pk_bf16(bflo(rv[i][j]) * d, bfhi(rv[i][j]) * d);
;             *(LAS u32x4*)(TVD + r * VSN + cc * 16) = vd; }
;         __syncthreads();
;         if (c + 1 < 16) RLN_LOAD(c + 1);
; #pragma unroll
;         for (int i = 0; i < 2; ++i)
; #pragma unroll
;             for (int nt = 0; nt < NT; ++nt) R[i][nt] = R[i][nt] * g64;
; #pragma unroll
;         for (int ks = 0; ks < 2; ++ks) {
;             const bf16x8 a0 = trfrag(TK, QS, 32 * ks, 16 * (2 * w), lane), a1 = trfrag(TK, QS, 32 * ks, 16 * (2 * w + 1), lane);
; #pragma unroll
;             for (int nt = 0; nt < NT; ++nt) { const bf16x8 bv = trfrag(TVD, VSN, 32 * ks, 16 * nt, lane); R[0][nt] = mfma16(a0, bv, R[0][nt]); R[1][nt] = mfma16(a1, bv, R[1][nt]); }
	s_waitcnt vmcnt(7)
	ds_write_b128 v197, v[136:139]
	s_waitcnt vmcnt(6)
	ds_write_b128 v198, v[140:143]
	s_waitcnt vmcnt(5)
	ds_write_b128 v199, v[148:151]
	s_waitcnt vmcnt(4)
	ds_write_b128 v200, v[152:155]
	s_waitcnt vmcnt(3)
	v_lshlrev_b32_e32 v136, 16, v156
	v_and_b32_e32 v137, 0xffff0000, v156
	v_lshlrev_b32_e32 v138, 16, v157
	v_and_b32_e32 v139, 0xffff0000, v157
	v_pk_mul_f32 v[136:137], v[170:171], v[136:137]
	v_pk_mul_f32 v[138:139], v[170:171], v[138:139]
	v_cvt_pk_bf16_f32 v136, v136, v137
	v_cvt_pk_bf16_f32 v137, v138, v139
	v_lshlrev_b32_e32 v138, 16, v158
	v_and_b32_e32 v139, 0xffff0000, v158
	v_lshlrev_b32_e32 v140, 16, v159
	v_and_b32_e32 v141, 0xffff0000, v159
	v_pk_mul_f32 v[138:139], v[170:171], v[138:139]
	v_pk_mul_f32 v[140:141], v[170:171], v[140:141]
	v_cvt_pk_bf16_f32 v138, v138, v139
	v_cvt_pk_bf16_f32 v139, v140, v141
	ds_write_b128 v196, v[136:139] offset:34816
	s_waitcnt vmcnt(2)
	v_lshlrev_b32_e32 v136, 16, v132
	v_and_b32_e32 v137, 0xffff0000, v132
	v_pk_mul_f32 v[136:137], v[168:169], v[136:137]
	v_pk_mul_f32 v[106:107], v[160:161], v[106:107]
	v_cvt_pk_bf16_f32 v132, v136, v137
	v_lshlrev_b32_e32 v136, 16, v133
	v_and_b32_e32 v137, 0xffff0000, v133
	v_pk_mul_f32 v[136:137], v[168:169], v[136:137]
	v_pk_mul_f32 v[104:105], v[162:163], v[104:105]
	v_cvt_pk_bf16_f32 v133, v136, v137
	v_lshlrev_b32_e32 v136, 16, v134
	v_and_b32_e32 v137, 0xffff0000, v134
	v_pk_mul_f32 v[136:137], v[168:169], v[136:137]
	v_pk_mul_f32 v[122:123], v[160:161], v[122:123]
	v_cvt_pk_bf16_f32 v134, v136, v137
	v_lshlrev_b32_e32 v136, 16, v135
	v_and_b32_e32 v137, 0xffff0000, v135
	v_pk_mul_f32 v[136:137], v[168:169], v[136:137]
	v_pk_mul_f32 v[120:121], v[162:163], v[120:121]
	v_cvt_pk_bf16_f32 v135, v136, v137
	ds_write_b128 v195, v[132:135] offset:34816
	s_waitcnt vmcnt(1)
	v_lshlrev_b32_e32 v132, 16, v128
	v_and_b32_e32 v133, 0xffff0000, v128
	v_pk_mul_f32 v[132:133], v[166:167], v[132:133]
	v_pk_mul_f32 v[102:103], v[160:161], v[102:103]
	v_cvt_pk_bf16_f32 v128, v132, v133
	v_lshlrev_b32_e32 v132, 16, v129
	v_and_b32_e32 v133, 0xffff0000, v129
	v_pk_mul_f32 v[132:133], v[166:167], v[132:133]
	v_pk_mul_f32 v[100:101], v[162:163], v[100:101]
	v_cvt_pk_bf16_f32 v129, v132, v133
	v_lshlrev_b32_e32 v132, 16, v130
	v_and_b32_e32 v133, 0xffff0000, v130
	v_pk_mul_f32 v[132:133], v[166:167], v[132:133]
	v_pk_mul_f32 v[114:115], v[160:161], v[114:115]
	v_cvt_pk_bf16_f32 v130, v132, v133
	v_lshlrev_b32_e32 v132, 16, v131
	v_and_b32_e32 v133, 0xffff0000, v131
	v_pk_mul_f32 v[132:133], v[166:167], v[132:133]
	v_pk_mul_f32 v[112:113], v[162:163], v[112:113]
	v_cvt_pk_bf16_f32 v131, v132, v133
	ds_write_b128 v194, v[128:131] offset:34816
	s_waitcnt vmcnt(0)
	v_lshlrev_b32_e32 v128, 16, v124
	v_and_b32_e32 v129, 0xffff0000, v124
	v_pk_mul_f32 v[128:129], v[164:165], v[128:129]
	v_pk_mul_f32 v[98:99], v[160:161], v[98:99]
	v_cvt_pk_bf16_f32 v124, v128, v129
	v_lshlrev_b32_e32 v128, 16, v125
	v_and_b32_e32 v129, 0xffff0000, v125
	v_pk_mul_f32 v[128:129], v[164:165], v[128:129]
	v_pk_mul_f32 v[96:97], v[162:163], v[96:97]
	v_cvt_pk_bf16_f32 v125, v128, v129
	v_lshlrev_b32_e32 v128, 16, v126
	v_and_b32_e32 v129, 0xffff0000, v126
	v_pk_mul_f32 v[128:129], v[164:165], v[128:129]
	v_pk_mul_f32 v[110:111], v[160:161], v[110:111]
	v_cvt_pk_bf16_f32 v126, v128, v129
	v_lshlrev_b32_e32 v128, 16, v127
	v_and_b32_e32 v129, 0xffff0000, v127
	v_pk_mul_f32 v[128:129], v[164:165], v[128:129]
	v_pk_mul_f32 v[108:109], v[162:163], v[108:109]
	v_cvt_pk_bf16_f32 v127, v128, v129
	ds_write_b128 v193, v[124:127] offset:34816
	s_waitcnt lgkmcnt(0)
	s_barrier
	v_pk_mul_f32 v[126:127], v[160:161], v[146:147]
	v_pk_mul_f32 v[124:125], v[162:163], v[144:145]
	ds_read_b64_tr_b16 v[130:131], v180 offset:2176
	ds_read_b64_tr_b16 v[128:129], v180
	ds_read_b64_tr_b16 v[134:135], v180 offset:2208
	ds_read_b64_tr_b16 v[132:133], v180 offset:32
	ds_read_b64_tr_b16 v[138:139], v192 offset:36992
	ds_read_b64_tr_b16 v[136:137], v192 offset:34816
	ds_read_b64_tr_b16 v[140:141], v192 offset:34848
	ds_read_b64_tr_b16 v[144:145], v192 offset:34880
	ds_read_b64_tr_b16 v[148:149], v192 offset:34912
	ds_read_b64_tr_b16 v[142:143], v192 offset:37024
	ds_read_b64_tr_b16 v[146:147], v192 offset:37056
	ds_read_b64_tr_b16 v[150:151], v192 offset:37088
	v_pk_mul_f32 v[90:91], v[160:161], v[90:91]
	v_pk_mul_f32 v[88:89], v[162:163], v[88:89]
	s_waitcnt lgkmcnt(6)
	v_mfma_f32_16x16x32_bf16 v[124:127], v[128:131], v[136:139], v[124:127]
	v_mul_f32_e64 v118, v160, v118
	v_mul_f32_e64 v119, v161, v119
	v_pk_mul_f32 v[116:117], v[162:163], v[116:117]
	v_pk_mul_f32 v[74:75], v[160:161], v[74:75]
	v_mfma_f32_16x16x32_bf16 v[104:107], v[132:135], v[136:139], v[104:107]
	v_mul_f32_e64 v72, v162, v72
	v_mul_f32_e64 v73, v163, v73
	v_pk_mul_f32 v[94:95], v[160:161], v[94:95]
	v_pk_mul_f32 v[92:93], v[162:163], v[92:93]
	s_waitcnt lgkmcnt(2)
	v_mfma_f32_16x16x32_bf16 v[120:123], v[128:131], v[140:143], v[120:123]
	v_mul_f32_e64 v70, v160, v70
	v_mul_f32_e64 v71, v161, v71
	v_pk_mul_f32 v[68:69], v[162:163], v[68:69]
	v_pk_mul_f32 v[82:83], v[160:161], v[82:83]
	v_mfma_f32_16x16x32_bf16 v[100:103], v[132:135], v[140:143], v[100:103]
	v_mul_f32_e64 v80, v162, v80
	v_mul_f32_e64 v81, v163, v81
	v_pk_mul_f32 v[66:67], v[160:161], v[66:67]
	v_pk_mul_f32 v[64:65], v[162:163], v[64:65]
	s_waitcnt lgkmcnt(1)
	v_mfma_f32_16x16x32_bf16 v[112:115], v[128:131], v[144:147], v[112:115]
	v_mul_f32_e64 v78, v160, v78
	v_mul_f32_e64 v79, v161, v79
	v_pk_mul_f32 v[76:77], v[162:163], v[76:77]
	v_pk_mul_f32 v[58:59], v[160:161], v[58:59]
	v_mfma_f32_16x16x32_bf16 v[96:99], v[132:135], v[144:147], v[96:99]
	v_mul_f32_e64 v56, v162, v56
	v_mul_f32_e64 v57, v163, v57
	v_pk_mul_f32 v[86:87], v[160:161], v[86:87]
	v_pk_mul_f32 v[84:85], v[162:163], v[84:85]
	s_waitcnt lgkmcnt(0)
; __device__ __forceinline__ f32x4 mfma16(bf16x8 a, bf16x8 b, f32x4 c) { return __builtin_amdgcn_mfma_f32_16x16x32_bf16(a, b, c, 0, 0, 0); }
; template <int NS> __device__ __forceinline__ void ret_local_unitN(LAS unsigned char* lds, const Params& P, int unit) {
;     ...
;     float* st = (float*)(P.ws + WS_RST) + ((size_t)(h * 16 + sc) * 8 + NS * grp) * 16384;
;     ...
;         for (int i = 0; i < 2; ++i)
; #pragma unroll
;             for (int nt = 0; nt < NT; ++nt) R[i][nt] = R[i][nt] * g64;
; #pragma unroll
;         for (int ks = 0; ks < 2; ++ks) {
;             const bf16x8 a0 = trfrag(TK, QS, 32 * ks, 16 * (2 * w), lane), a1 = trfrag(TK, QS, 32 * ks, 16 * (2 * w + 1), lane);
; #pragma unroll
;             for (int nt = 0; nt < NT; ++nt) { const bf16x8 bv = trfrag(TVD, VSN, 32 * ks, 16 * nt, lane); R[0][nt] = mfma16(a0, bv, R[0][nt]); R[1][nt] = mfma16(a1, bv, R[1][nt]); }
	v_mfma_f32_16x16x32_bf16 v[108:111], v[128:131], v[148:151], v[108:111]
	v_mul_f32_e64 v42, v160, v42
	v_mul_f32_e64 v43, v161, v43
	v_pk_mul_f32 v[40:41], v[162:163], v[40:41]
	v_pk_mul_f32 v[62:63], v[160:161], v[62:63]
	v_mfma_f32_16x16x32_bf16 v[88:91], v[132:135], v[148:151], v[88:91]
	ds_read_b64_tr_b16 v[138:139], v192 offset:37120
	ds_read_b64_tr_b16 v[136:137], v192 offset:34944
	ds_read_b64_tr_b16 v[140:141], v192 offset:34976
	ds_read_b64_tr_b16 v[144:145], v192 offset:35008
	ds_read_b64_tr_b16 v[148:149], v192 offset:35040
	ds_read_b64_tr_b16 v[142:143], v192 offset:37152
	ds_read_b64_tr_b16 v[146:147], v192 offset:37184
	ds_read_b64_tr_b16 v[150:151], v192 offset:37216
	v_pk_mul_f32 v[60:61], v[162:163], v[60:61]
	v_pk_mul_f32 v[38:39], v[160:161], v[38:39]
	s_waitcnt lgkmcnt(6)
	v_mfma_f32_16x16x32_bf16 v[116:119], v[128:131], v[136:139], v[116:119]
	v_mul_f32_e64 v36, v162, v36
	v_mul_f32_e64 v37, v163, v37
	v_pk_mul_f32 v[50:51], v[160:161], v[50:51]
	v_pk_mul_f32 v[48:49], v[162:163], v[48:49]
	v_mfma_f32_16x16x32_bf16 v[72:75], v[132:135], v[136:139], v[72:75]
	v_mul_f32_e64 v34, v160, v34
	v_mul_f32_e64 v35, v161, v35
	v_pk_mul_f32 v[32:33], v[162:163], v[32:33]
	v_pk_mul_f32 v[46:47], v[160:161], v[46:47]
	s_waitcnt lgkmcnt(2)
	v_mfma_f32_16x16x32_bf16 v[92:95], v[128:131], v[140:143], v[92:95]
	v_mul_f32_e64 v44, v162, v44
	v_mul_f32_e64 v45, v163, v45
	v_pk_mul_f32 v[26:27], v[160:161], v[26:27]
	v_pk_mul_f32 v[24:25], v[162:163], v[24:25]
	v_mfma_f32_16x16x32_bf16 v[68:71], v[132:135], v[140:143], v[68:71]
	v_mul_f32_e64 v10, v160, v10
	v_mul_f32_e64 v11, v161, v11
	v_pk_mul_f32 v[8:9], v[162:163], v[8:9]
	v_pk_mul_f32 v[14:15], v[160:161], v[14:15]
	s_waitcnt lgkmcnt(1)
	v_mfma_f32_16x16x32_bf16 v[80:83], v[128:131], v[144:147], v[80:83]
	v_mul_f32_e64 v12, v162, v12
	v_mul_f32_e64 v13, v163, v13
	v_pk_mul_f32 v[6:7], v[160:161], v[6:7]
	v_pk_mul_f32 v[4:5], v[162:163], v[4:5]
	v_mfma_f32_16x16x32_bf16 v[64:67], v[132:135], v[144:147], v[64:67]
	v_mul_f32_e64 v2, v160, v2
	v_mul_f32_e64 v3, v161, v3
	v_pk_mul_f32 v[0:1], v[162:163], v[0:1]
	s_lshl_b32 s0, s17, 4
	s_waitcnt lgkmcnt(0)
	v_mfma_f32_16x16x32_bf16 v[76:79], v[128:131], v[148:151], v[76:79]
	s_or_b32 s0, s0, s16
	s_ashr_i32 s1, s0, 31
	s_lshl_b64 s[0:1], s[0:1], 19
	v_mfma_f32_16x16x32_bf16 v[56:59], v[132:135], v[148:151], v[56:59]
	ds_read_b64_tr_b16 v[138:139], v192 offset:37248
	ds_read_b64_tr_b16 v[136:137], v192 offset:35072
	ds_read_b64_tr_b16 v[140:141], v192 offset:35104
	ds_read_b64_tr_b16 v[144:145], v192 offset:35136
	ds_read_b64_tr_b16 v[148:149], v192 offset:35168
	ds_read_b64_tr_b16 v[142:143], v192 offset:37280
	ds_read_b64_tr_b16 v[146:147], v192 offset:37312
	ds_read_b64_tr_b16 v[150:151], v192 offset:37344
	s_add_u32 s10, s94, s0
	s_addc_u32 s11, s75, s1
	s_waitcnt lgkmcnt(6)
	v_mfma_f32_16x16x32_bf16 v[84:87], v[128:131], v[136:139], v[84:87]
	s_lshl_b32 s0, s3, 2
	s_ashr_i32 s1, s0, 31
	s_lshl_b64 s[0:1], s[0:1], 16
	v_mfma_f32_16x16x32_bf16 v[40:43], v[132:135], v[136:139], v[40:43]
	s_add_u32 s0, s10, s0
	s_addc_u32 s1, s11, s1
	s_add_i32 s2, s2, s70
	s_waitcnt lgkmcnt(2)
	v_mfma_f32_16x16x32_bf16 v[60:63], v[128:131], v[140:143], v[60:63]
	s_cmpk_gt_i32 s2, 0xff
	v_mfma_f32_16x16x32_bf16 v[36:39], v[132:135], v[140:143], v[36:39]
	v_mul_f32_e64 v142, v160, v54
	v_mul_f32_e64 v143, v161, v55
	v_pk_mul_f32 v[140:141], v[162:163], v[52:53]
	s_waitcnt lgkmcnt(1)
	v_mfma_f32_16x16x32_bf16 v[48:51], v[128:131], v[144:147], v[48:51]
	v_mfma_f32_16x16x32_bf16 v[32:35], v[132:135], v[144:147], v[32:35]
	s_waitcnt lgkmcnt(0)
	v_mfma_f32_16x16x32_bf16 v[136:139], v[128:131], v[148:151], v[44:47]
	v_mfma_f32_16x16x32_bf16 v[52:55], v[132:135], v[148:151], v[24:27]
	s_nop 2
	ds_read_b64_tr_b16 v[26:27], v192 offset:37376
	ds_read_b64_tr_b16 v[24:25], v192 offset:35200
	ds_read_b64_tr_b16 v[44:45], v192 offset:35232
	ds_read_b64_tr_b16 v[144:145], v192 offset:35264
	ds_read_b64_tr_b16 v[148:149], v192 offset:35296
	ds_read_b64_tr_b16 v[46:47], v192 offset:37408
	ds_read_b64_tr_b16 v[146:147], v192 offset:37440
	ds_read_b64_tr_b16 v[150:151], v192 offset:37472
	s_waitcnt lgkmcnt(2)
	v_mfma_f32_16x16x32_bf16 v[164:167], v[132:135], v[44:47], v[8:11]
	s_nop 2
	v_mul_f32_e64 v10, v160, v22
	v_mul_f32_e64 v11, v161, v23
	v_pk_mul_f32 v[8:9], v[162:163], v[20:21]
	v_mfma_f32_16x16x32_bf16 v[152:155], v[132:135], v[24:27], v[12:15]
	s_nop 2
	v_mul_f32_e64 v14, v160, v30
	v_mul_f32_e64 v15, v161, v31
	v_pk_mul_f32 v[12:13], v[162:163], v[28:29]
	s_waitcnt lgkmcnt(1)
	v_mfma_f32_16x16x32_bf16 v[168:171], v[128:131], v[144:147], v[8:11]
	v_mfma_f32_16x16x32_bf16 v[144:147], v[132:135], v[144:147], v[4:7]
	s_nop 2
	v_mul_f32_e64 v6, v160, v18
	v_mul_f32_e64 v7, v161, v19
	v_pk_mul_f32 v[4:5], v[162:163], v[16:17]
	v_mfma_f32_16x16x32_bf16 v[140:143], v[128:131], v[24:27], v[140:143]
	v_mfma_f32_16x16x32_bf16 v[156:159], v[128:131], v[44:47], v[12:15]
	s_waitcnt lgkmcnt(0)
	v_mfma_f32_16x16x32_bf16 v[128:131], v[128:131], v[148:151], v[4:7]
	v_mfma_f32_16x16x32_bf16 v[132:135], v[132:135], v[148:151], v[0:3]
	ds_read_b64_tr_b16 v[148:149], v180 offset:17408
	ds_read_b64_tr_b16 v[150:151], v180 offset:19584
	ds_read_b64_tr_b16 v[162:163], v180 offset:19616
	ds_read_b64_tr_b16 v[160:161], v180 offset:17440
	ds_read_b64_tr_b16 v[2:3], v192 offset:54400
	ds_read_b64_tr_b16 v[0:1], v192 offset:52224
	ds_read_b64_tr_b16 v[4:5], v192 offset:52256
	ds_read_b64_tr_b16 v[16:17], v192 offset:52288
	ds_read_b64_tr_b16 v[20:21], v192 offset:52320
	ds_read_b64_tr_b16 v[6:7], v192 offset:54432
	ds_read_b64_tr_b16 v[18:19], v192 offset:54464
	ds_read_b64_tr_b16 v[22:23], v192 offset:54496
	s_waitcnt lgkmcnt(6)
; __device__ __forceinline__ f32x4 mfma16(bf16x8 a, bf16x8 b, f32x4 c) { return __builtin_amdgcn_mfma_f32_16x16x32_bf16(a, b, c, 0, 0, 0); }
; template <int NS> __device__ __forceinline__ void ret_local_unitN(LAS unsigned char* lds, const Params& P, int unit) {
;     ...
;         for (int ks = 0; ks < 2; ++ks) {
;             const bf16x8 a0 = trfrag(TK, QS, 32 * ks, 16 * (2 * w), lane), a1 = trfrag(TK, QS, 32 * ks, 16 * (2 * w + 1), lane);
; #pragma unroll
;             for (int nt = 0; nt < NT; ++nt) { const bf16x8 bv = trfrag(TVD, VSN, 32 * ks, 16 * nt, lane); R[0][nt] = mfma16(a0, bv, R[0][nt]); R[1][nt] = mfma16(a1, bv, R[1][nt]); }
;         }
;         __syncthreads();
;     }
; #pragma unroll
;     for (int i = 0; i < 2; ++i)
; #pragma unroll
;         for (int nt = 0; nt < NT; ++nt)
; #pragma unroll
;             for (int r = 0; r < 4; ++r) st[(size_t)(nt >> 2) * 16384 + (16 * (2 * w + i) + 4 * quad + r) * 64 + 16 * (nt & 3) + l15] = R[i][nt][r];
	v_mfma_f32_16x16x32_bf16 v[124:127], v[148:151], v[0:3], v[124:127]
	v_mfma_f32_16x16x32_bf16 v[12:15], v[160:163], v[0:3], v[104:107]
	s_waitcnt lgkmcnt(2)
	v_mfma_f32_16x16x32_bf16 v[104:107], v[148:151], v[4:7], v[120:123]
	v_mfma_f32_16x16x32_bf16 v[8:11], v[160:163], v[4:7], v[100:103]
	s_waitcnt lgkmcnt(1)
	v_mfma_f32_16x16x32_bf16 v[100:103], v[148:151], v[16:19], v[112:115]
	v_mfma_f32_16x16x32_bf16 v[4:7], v[160:163], v[16:19], v[96:99]
	s_waitcnt lgkmcnt(0)
	v_mfma_f32_16x16x32_bf16 v[96:99], v[148:151], v[20:23], v[108:111]
	v_mfma_f32_16x16x32_bf16 v[0:3], v[160:163], v[20:23], v[88:91]
	ds_read_b64_tr_b16 v[18:19], v192 offset:54528
	ds_read_b64_tr_b16 v[16:17], v192 offset:52352
	ds_read_b64_tr_b16 v[20:21], v192 offset:52384
	ds_read_b64_tr_b16 v[44:45], v192 offset:52416
	ds_read_b64_tr_b16 v[88:89], v192 offset:52448
	ds_read_b64_tr_b16 v[22:23], v192 offset:54560
	ds_read_b64_tr_b16 v[46:47], v192 offset:54592
	ds_read_b64_tr_b16 v[90:91], v192 offset:54624
	s_waitcnt lgkmcnt(6)
	v_mfma_f32_16x16x32_bf16 v[108:111], v[148:151], v[16:19], v[116:119]
	v_mfma_f32_16x16x32_bf16 v[28:31], v[160:163], v[16:19], v[72:75]
	s_waitcnt lgkmcnt(2)
	v_mfma_f32_16x16x32_bf16 v[72:75], v[148:151], v[20:23], v[92:95]
	v_mfma_f32_16x16x32_bf16 v[24:27], v[160:163], v[20:23], v[68:71]
	s_waitcnt lgkmcnt(1)
	v_mfma_f32_16x16x32_bf16 v[68:71], v[148:151], v[44:47], v[80:83]
	v_mfma_f32_16x16x32_bf16 v[20:23], v[160:163], v[44:47], v[64:67]
	s_waitcnt lgkmcnt(0)
	v_mfma_f32_16x16x32_bf16 v[64:67], v[148:151], v[88:91], v[76:79]
	v_mfma_f32_16x16x32_bf16 v[16:19], v[160:163], v[88:91], v[56:59]
	ds_read_b64_tr_b16 v[46:47], v192 offset:54656
	ds_read_b64_tr_b16 v[44:45], v192 offset:52480
	s_nop 0
	ds_read_b64_tr_b16 v[56:57], v192 offset:52512
	ds_read_b64_tr_b16 v[76:77], v192 offset:52544
	ds_read_b64_tr_b16 v[80:81], v192 offset:52576
	ds_read_b64_tr_b16 v[58:59], v192 offset:54688
	ds_read_b64_tr_b16 v[78:79], v192 offset:54720
	ds_read_b64_tr_b16 v[82:83], v192 offset:54752
	s_waitcnt lgkmcnt(6)
	v_mfma_f32_16x16x32_bf16 v[84:87], v[148:151], v[44:47], v[84:87]
	v_mfma_f32_16x16x32_bf16 v[44:47], v[160:163], v[44:47], v[40:43]
	s_waitcnt lgkmcnt(2)
	v_mfma_f32_16x16x32_bf16 v[88:91], v[148:151], v[56:59], v[60:63]
	v_mfma_f32_16x16x32_bf16 v[40:43], v[160:163], v[56:59], v[36:39]
	s_waitcnt lgkmcnt(1)
	v_mfma_f32_16x16x32_bf16 v[92:95], v[148:151], v[76:79], v[48:51]
	v_mfma_f32_16x16x32_bf16 v[36:39], v[160:163], v[76:79], v[32:35]
	s_waitcnt lgkmcnt(0)
	v_mfma_f32_16x16x32_bf16 v[76:79], v[148:151], v[80:83], v[136:139]
	v_mfma_f32_16x16x32_bf16 v[32:35], v[160:163], v[80:83], v[52:55]
	ds_read_b64_tr_b16 v[50:51], v192 offset:54784
	ds_read_b64_tr_b16 v[48:49], v192 offset:52608
	s_nop 0
	ds_read_b64_tr_b16 v[52:53], v192 offset:52640
	ds_read_b64_tr_b16 v[60:61], v192 offset:52672
	ds_read_b64_tr_b16 v[80:81], v192 offset:52704
	ds_read_b64_tr_b16 v[54:55], v192 offset:54816
	ds_read_b64_tr_b16 v[62:63], v192 offset:54848
	ds_read_b64_tr_b16 v[82:83], v192 offset:54880
	v_and_b32_e32 v136, 15, v190
	v_lshlrev_b32_e32 v180, 2, v136
	s_waitcnt lgkmcnt(6)
	v_mfma_f32_16x16x32_bf16 v[112:115], v[148:151], v[48:51], v[140:143]
	s_waitcnt lgkmcnt(0)
	s_barrier
	v_mfma_f32_16x16x32_bf16 v[56:59], v[160:163], v[48:51], v[152:155]
	v_mfma_f32_16x16x32_bf16 v[116:119], v[148:151], v[52:55], v[156:159]
	v_mfma_f32_16x16x32_bf16 v[48:51], v[160:163], v[52:55], v[164:167]
	v_mfma_f32_16x16x32_bf16 v[120:123], v[148:151], v[60:63], v[168:171]
	v_mfma_f32_16x16x32_bf16 v[52:55], v[160:163], v[60:63], v[144:147]
	v_mfma_f32_16x16x32_bf16 v[128:131], v[148:151], v[80:83], v[128:131]
	v_mfma_f32_16x16x32_bf16 v[60:63], v[160:163], v[80:83], v[132:135]
	v_and_or_b32 v82, v191, 12, s20
	v_lshlrev_b32_e32 v82, 6, v82
	v_ashrrev_i32_e32 v83, 31, v82
	v_lshl_add_u64 v[80:81], s[0:1], 0, v[180:181]
	v_lshlrev_b64 v[132:133], 2, v[82:83]
	v_lshl_add_u64 v[134:135], v[80:81], 0, v[132:133]
	s_mov_b64 s[0:1], 0xc0
	global_store_dword v[134:135], v124, off
	global_store_dword v[134:135], v125, off offset:256
	global_store_dword v[134:135], v126, off offset:512
	global_store_dword v[134:135], v127, off offset:768
	global_store_dword v[134:135], v104, off offset:64
	global_store_dword v[134:135], v105, off offset:320
	global_store_dword v[134:135], v106, off offset:576
	global_store_dword v[134:135], v107, off offset:832
	global_store_dword v[134:135], v100, off offset:128
	global_store_dword v[134:135], v101, off offset:384
	global_store_dword v[134:135], v102, off offset:640
	global_store_dword v[134:135], v103, off offset:896
	v_lshl_add_u64 v[100:101], v[80:81], 0, s[0:1]
	s_mov_b64 s[0:1], 0x10000
	global_store_dword v[134:135], v96, off offset:192
	global_store_dword v[134:135], v97, off offset:448
	global_store_dword v[134:135], v98, off offset:704
	global_store_dword v[134:135], v99, off offset:960
	v_lshl_add_u64 v[96:97], v[80:81], 0, s[0:1]
	v_lshl_add_u64 v[98:99], v[96:97], 0, v[132:133]
	s_mov_b64 s[0:1], 0x10040
	global_store_dword v[98:99], v108, off
	global_store_dword v[98:99], v109, off offset:256
	global_store_dword v[98:99], v110, off offset:512
	global_store_dword v[98:99], v111, off offset:768
	v_lshl_add_u64 v[98:99], v[80:81], 0, s[0:1]
	v_lshl_add_u64 v[102:103], v[98:99], 0, v[132:133]
	s_mov_b64 s[0:1], 0x10080
	global_store_dword v[102:103], v72, off
	global_store_dword v[102:103], v73, off offset:256
	global_store_dword v[102:103], v74, off offset:512
	global_store_dword v[102:103], v75, off offset:768
	v_lshl_add_u64 v[72:73], v[80:81], 0, s[0:1]
	v_lshl_add_u64 v[74:75], v[72:73], 0, v[132:133]
	s_mov_b64 s[0:1], 0x100c0
; template <int NS> __device__ __forceinline__ void ret_local_unitN(LAS unsigned char* lds, const Params& P, int unit) {
;     ...
; #pragma unroll
;     for (int i = 0; i < 2; ++i)
; #pragma unroll
;         for (int nt = 0; nt < NT; ++nt)
; #pragma unroll
;             for (int r = 0; r < 4; ++r) st[(size_t)(nt >> 2) * 16384 + (16 * (2 * w + i) + 4 * quad + r) * 64 + 16 * (nt & 3) + l15] = R[i][nt][r];
	global_store_dword v[74:75], v68, off
	global_store_dword v[74:75], v69, off offset:256
	global_store_dword v[74:75], v70, off offset:512
	global_store_dword v[74:75], v71, off offset:768
	v_lshl_add_u64 v[68:69], v[80:81], 0, s[0:1]
	v_lshl_add_u64 v[70:71], v[68:69], 0, v[132:133]
	s_mov_b64 s[0:1], 0x20000
	global_store_dword v[70:71], v64, off
	global_store_dword v[70:71], v65, off offset:256
	global_store_dword v[70:71], v66, off offset:512
	global_store_dword v[70:71], v67, off offset:768
	v_lshl_add_u64 v[64:65], v[80:81], 0, s[0:1]
	v_lshl_add_u64 v[66:67], v[64:65], 0, v[132:133]
	s_mov_b64 s[0:1], 0x20040
	global_store_dword v[66:67], v84, off
	global_store_dword v[66:67], v85, off offset:256
	global_store_dword v[66:67], v86, off offset:512
	global_store_dword v[66:67], v87, off offset:768
	v_lshl_add_u64 v[66:67], v[80:81], 0, s[0:1]
	v_lshl_add_u64 v[70:71], v[66:67], 0, v[132:133]
	s_mov_b64 s[0:1], 0x20080
	global_store_dword v[70:71], v88, off
	global_store_dword v[70:71], v89, off offset:256
	global_store_dword v[70:71], v90, off offset:512
	global_store_dword v[70:71], v91, off offset:768
	v_lshl_add_u64 v[70:71], v[80:81], 0, s[0:1]
	v_lshl_add_u64 v[74:75], v[70:71], 0, v[132:133]
	s_mov_b64 s[0:1], 0x200c0
	global_store_dword v[74:75], v92, off
	global_store_dword v[74:75], v93, off offset:256
	global_store_dword v[74:75], v94, off offset:512
	global_store_dword v[74:75], v95, off offset:768
	v_lshl_add_u64 v[74:75], v[80:81], 0, s[0:1]
	v_lshl_add_u64 v[84:85], v[74:75], 0, v[132:133]
	s_mov_b64 s[0:1], 0x30000
	global_store_dword v[84:85], v76, off
	global_store_dword v[84:85], v77, off offset:256
	global_store_dword v[84:85], v78, off offset:512
	global_store_dword v[84:85], v79, off offset:768
	v_lshl_add_u64 v[76:77], v[80:81], 0, s[0:1]
	v_lshl_add_u64 v[78:79], v[76:77], 0, v[132:133]
	s_mov_b64 s[0:1], 0x30040
	global_store_dword v[78:79], v112, off
	global_store_dword v[78:79], v113, off offset:256
	global_store_dword v[78:79], v114, off offset:512
	global_store_dword v[78:79], v115, off offset:768
	v_lshl_add_u64 v[78:79], v[80:81], 0, s[0:1]
	v_lshl_add_u64 v[84:85], v[78:79], 0, v[132:133]
	s_mov_b64 s[0:1], 0x30080
	global_store_dword v[84:85], v116, off
	global_store_dword v[84:85], v117, off offset:256
	global_store_dword v[84:85], v118, off offset:512
	global_store_dword v[84:85], v119, off offset:768
	v_lshl_add_u64 v[84:85], v[80:81], 0, s[0:1]
	v_lshl_add_u64 v[86:87], v[84:85], 0, v[132:133]
	s_mov_b64 s[0:1], 0x300c0
	global_store_dword v[86:87], v120, off
	global_store_dword v[86:87], v121, off offset:256
	global_store_dword v[86:87], v122, off offset:512
	global_store_dword v[86:87], v123, off offset:768
	v_lshl_add_u64 v[86:87], v[80:81], 0, s[0:1]
	v_lshl_add_u64 v[88:89], v[86:87], 0, v[132:133]
	global_store_dword v[88:89], v128, off
	global_store_dword v[88:89], v129, off offset:256
	global_store_dword v[88:89], v130, off offset:512
	global_store_dword v[88:89], v131, off offset:768
	v_or_b32_e32 v88, 0x400, v82
	v_ashrrev_i32_e32 v89, 31, v88
	v_lshlrev_b64 v[88:89], 2, v[88:89]
	v_lshl_add_u64 v[90:91], v[80:81], 0, v[88:89]
	global_store_dword v[90:91], v12, off
	v_or_b32_e32 v90, 0x440, v82
	v_ashrrev_i32_e32 v91, 31, v90
	v_lshlrev_b64 v[90:91], 2, v[90:91]
	v_lshl_add_u64 v[92:93], v[80:81], 0, v[90:91]
	v_or_b32_e32 v12, 0x480, v82
	v_or_b32_e32 v82, 0x4c0, v82
	global_store_dword v[92:93], v13, off
	v_ashrrev_i32_e32 v13, 31, v12
	v_ashrrev_i32_e32 v83, 31, v82
	v_lshlrev_b64 v[12:13], 2, v[12:13]
	v_lshlrev_b64 v[82:83], 2, v[82:83]
	v_lshl_add_u64 v[124:125], v[80:81], 0, 64
	v_lshl_add_u64 v[104:105], v[80:81], 0, s[8:9]
	v_lshl_add_u64 v[92:93], v[80:81], 0, v[12:13]
	v_lshl_add_u64 v[80:81], v[80:81], 0, v[82:83]
	global_store_dword v[92:93], v14, off
	global_store_dword v[80:81], v15, off
	v_lshl_add_u64 v[14:15], v[124:125], 0, v[88:89]
	global_store_dword v[14:15], v8, off
	v_lshl_add_u64 v[14:15], v[124:125], 0, v[90:91]
	global_store_dword v[14:15], v9, off
	v_lshl_add_u64 v[8:9], v[124:125], 0, v[12:13]
	global_store_dword v[8:9], v10, off
	v_lshl_add_u64 v[8:9], v[124:125], 0, v[82:83]
	global_store_dword v[8:9], v11, off
	v_lshl_add_u64 v[8:9], v[104:105], 0, v[88:89]
	global_store_dword v[8:9], v4, off
	v_lshl_add_u64 v[8:9], v[104:105], 0, v[90:91]
	global_store_dword v[8:9], v5, off
	v_lshl_add_u64 v[4:5], v[104:105], 0, v[12:13]
	global_store_dword v[4:5], v6, off
; template <int NS> __device__ __forceinline__ void ret_local_unitN(LAS unsigned char* lds, const Params& P, int unit) {
;     ...
; #pragma unroll
;     for (int i = 0; i < 2; ++i)
; #pragma unroll
;         for (int nt = 0; nt < NT; ++nt)
; #pragma unroll
;             for (int r = 0; r < 4; ++r) st[(size_t)(nt >> 2) * 16384 + (16 * (2 * w + i) + 4 * quad + r) * 64 + 16 * (nt & 3) + l15] = R[i][nt][r];
; __global__ void __launch_bounds__(512) mk_fwd(Params P) {
;     ...
;         else if (EN_RET && (ph == 16 || ph == 23)) { for (int u = vcu; u < 256; u += G) ret_local_unitN<4>(lds, P, u); }
	v_lshl_add_u64 v[4:5], v[104:105], 0, v[82:83]
	global_store_dword v[4:5], v7, off
	v_lshl_add_u64 v[4:5], v[100:101], 0, v[88:89]
	global_store_dword v[4:5], v0, off
	v_lshl_add_u64 v[4:5], v[100:101], 0, v[90:91]
	global_store_dword v[4:5], v1, off
	v_lshl_add_u64 v[0:1], v[100:101], 0, v[12:13]
	global_store_dword v[0:1], v2, off
	v_lshl_add_u64 v[0:1], v[100:101], 0, v[82:83]
	global_store_dword v[0:1], v3, off
	v_lshl_add_u64 v[0:1], v[96:97], 0, v[88:89]
	global_store_dword v[0:1], v28, off
	v_lshl_add_u64 v[0:1], v[96:97], 0, v[90:91]
	global_store_dword v[0:1], v29, off
	v_lshl_add_u64 v[0:1], v[96:97], 0, v[12:13]
	global_store_dword v[0:1], v30, off
	v_lshl_add_u64 v[0:1], v[96:97], 0, v[82:83]
	global_store_dword v[0:1], v31, off
	v_lshl_add_u64 v[0:1], v[98:99], 0, v[88:89]
	global_store_dword v[0:1], v24, off
	v_lshl_add_u64 v[0:1], v[98:99], 0, v[90:91]
	global_store_dword v[0:1], v25, off
	v_lshl_add_u64 v[0:1], v[98:99], 0, v[12:13]
	global_store_dword v[0:1], v26, off
	v_lshl_add_u64 v[0:1], v[98:99], 0, v[82:83]
	global_store_dword v[0:1], v27, off
	v_lshl_add_u64 v[0:1], v[72:73], 0, v[88:89]
	global_store_dword v[0:1], v20, off
	v_lshl_add_u64 v[0:1], v[72:73], 0, v[90:91]
	global_store_dword v[0:1], v21, off
	v_lshl_add_u64 v[0:1], v[72:73], 0, v[12:13]
	global_store_dword v[0:1], v22, off
	v_lshl_add_u64 v[0:1], v[72:73], 0, v[82:83]
	global_store_dword v[0:1], v23, off
	v_lshl_add_u64 v[0:1], v[68:69], 0, v[88:89]
	global_store_dword v[0:1], v16, off
	v_lshl_add_u64 v[0:1], v[68:69], 0, v[90:91]
	global_store_dword v[0:1], v17, off
	v_lshl_add_u64 v[0:1], v[68:69], 0, v[12:13]
	global_store_dword v[0:1], v18, off
	v_lshl_add_u64 v[0:1], v[68:69], 0, v[82:83]
	global_store_dword v[0:1], v19, off
	v_lshl_add_u64 v[0:1], v[64:65], 0, v[88:89]
	global_store_dword v[0:1], v44, off
	v_lshl_add_u64 v[0:1], v[64:65], 0, v[90:91]
	global_store_dword v[0:1], v45, off
	v_lshl_add_u64 v[0:1], v[64:65], 0, v[12:13]
	global_store_dword v[0:1], v46, off
	v_lshl_add_u64 v[0:1], v[64:65], 0, v[82:83]
	global_store_dword v[0:1], v47, off
	v_lshl_add_u64 v[0:1], v[66:67], 0, v[88:89]
	global_store_dword v[0:1], v40, off
	v_lshl_add_u64 v[0:1], v[66:67], 0, v[90:91]
	global_store_dword v[0:1], v41, off
	v_lshl_add_u64 v[0:1], v[66:67], 0, v[12:13]
	global_store_dword v[0:1], v42, off
	v_lshl_add_u64 v[0:1], v[66:67], 0, v[82:83]
	global_store_dword v[0:1], v43, off
	v_lshl_add_u64 v[0:1], v[70:71], 0, v[88:89]
	global_store_dword v[0:1], v36, off
	v_lshl_add_u64 v[0:1], v[70:71], 0, v[90:91]
	global_store_dword v[0:1], v37, off
	v_lshl_add_u64 v[0:1], v[70:71], 0, v[12:13]
	global_store_dword v[0:1], v38, off
	v_lshl_add_u64 v[0:1], v[70:71], 0, v[82:83]
	global_store_dword v[0:1], v39, off
	v_lshl_add_u64 v[0:1], v[74:75], 0, v[88:89]
	global_store_dword v[0:1], v32, off
	v_lshl_add_u64 v[0:1], v[74:75], 0, v[90:91]
	global_store_dword v[0:1], v33, off
	v_lshl_add_u64 v[0:1], v[74:75], 0, v[12:13]
	global_store_dword v[0:1], v34, off
	v_lshl_add_u64 v[0:1], v[74:75], 0, v[82:83]
	global_store_dword v[0:1], v35, off
	v_lshl_add_u64 v[0:1], v[76:77], 0, v[88:89]
	global_store_dword v[0:1], v56, off
	v_lshl_add_u64 v[0:1], v[76:77], 0, v[90:91]
	global_store_dword v[0:1], v57, off
	v_lshl_add_u64 v[0:1], v[76:77], 0, v[12:13]
	global_store_dword v[0:1], v58, off
	v_lshl_add_u64 v[0:1], v[76:77], 0, v[82:83]
	global_store_dword v[0:1], v59, off
	v_lshl_add_u64 v[0:1], v[78:79], 0, v[88:89]
	global_store_dword v[0:1], v48, off
	v_lshl_add_u64 v[0:1], v[78:79], 0, v[90:91]
	global_store_dword v[0:1], v49, off
	v_lshl_add_u64 v[0:1], v[78:79], 0, v[12:13]
	global_store_dword v[0:1], v50, off
	v_lshl_add_u64 v[0:1], v[78:79], 0, v[82:83]
	global_store_dword v[0:1], v51, off
	v_lshl_add_u64 v[0:1], v[84:85], 0, v[88:89]
	global_store_dword v[0:1], v52, off
	v_lshl_add_u64 v[0:1], v[84:85], 0, v[90:91]
	global_store_dword v[0:1], v53, off
	v_lshl_add_u64 v[0:1], v[84:85], 0, v[12:13]
	global_store_dword v[0:1], v54, off
	v_lshl_add_u64 v[0:1], v[84:85], 0, v[82:83]
	global_store_dword v[0:1], v55, off
	v_lshl_add_u64 v[0:1], v[86:87], 0, v[88:89]
	global_store_dword v[0:1], v60, off
	v_lshl_add_u64 v[0:1], v[86:87], 0, v[90:91]
	global_store_dword v[0:1], v61, off
	v_lshl_add_u64 v[0:1], v[86:87], 0, v[12:13]
	global_store_dword v[0:1], v62, off
	v_lshl_add_u64 v[0:1], v[86:87], 0, v[82:83]
	global_store_dword v[0:1], v63, off
	s_cbranch_scc0 .LBB0_71
